# first k-loop iteration of each GEMM mainloop peeled with C=0 accumulators (128 zero-init v_movs per unit removed)
# speedup vs baseline: 1.0411x; 1.0042x over previous
.LBB0_211:
	s_add_i32 s60, s60, 1
	s_mov_b64 s[36:37], s[18:19]
	s_mul_i32 s18, s60, s26
	s_add_i32 s38, s18, s2
	s_cmpk_gt_i32 s38, 0x1ff
	s_cselect_b64 s[44:45], -1, 0
	s_lshl_b32 s18, s38, 3
	s_and_b32 s18, s18, 56
	s_bfe_u32 s19, s38, 0x30003
	s_mov_b32 s27, s61
	s_or_b32 s61, s18, s19
	s_mov_b32 s3, s42
	s_ashr_i32 s42, s38, 6
	s_lshl_b32 s18, s61, 19
	s_mov_b64 s[4:5], s[20:21]
	s_add_u32 s20, s14, s18
	s_addc_u32 s21, s15, 0
	s_ashr_i32 s43, s42, 31
	s_lshl_b64 s[18:19], s[42:43], 19
	s_add_u32 s18, s16, s18
	s_addc_u32 s19, s17, s19
	s_cmpk_lt_i32 s38, 0x200
	s_cselect_b32 s38, s21, s5
	s_cselect_b32 s43, s20, s4
	s_cselect_b32 s62, s19, s37
	s_cselect_b32 s63, s18, s36
	s_add_u32 s64, s36, 0x100
	s_addc_u32 s65, s37, 0
	s_mov_b32 s66, -2
	s_waitcnt lgkmcnt(0)
	s_add_u32 s36, s4, 0x100
	s_addc_u32 s37, s5, 0
	s_add_i32 s67, 0, 0x10000
	v_add_u32_e32 v1, s67, v191
	ds_read_b128 v[34:37], v1
	ds_read_b128 v[38:41], v1 offset:1024
	ds_read_b128 v[42:45], v1 offset:2048
	ds_read_b128 v[46:49], v1 offset:3072
	s_cmp_eq_u32 s66, 12
	s_cselect_b32 s49, s38, s37
	s_cselect_b32 s48, s43, s36
	s_cselect_b32 s47, s62, s65
	s_cselect_b32 s46, s63, s64
	v_lshl_add_u64 v[186:187], s[4:5], 0, v[168:169]
	s_add_i32 m0, s53, 0xc000
	ds_read_b128 v[50:53], v206
	ds_read_b128 v[58:61], v206 offset:1024
	ds_read_b128 v[62:65], v206 offset:2048
	ds_read_b128 v[66:69], v206 offset:3072
	ds_read_b128 v[170:173], v206 offset:4096
	ds_read_b128 v[174:177], v206 offset:5120
	ds_read_b128 v[178:181], v206 offset:6144
	ds_read_b128 v[182:185], v206 offset:7168
	global_load_lds_dwordx4 v[186:187], off
	v_lshl_add_u64 v[186:187], s[4:5], 0, v[166:167]
	s_add_i32 m0, s53, 0xe000
	s_nop 0
	global_load_lds_dwordx4 v[186:187], off
	s_waitcnt lgkmcnt(8)
	s_barrier
	s_waitcnt lgkmcnt(0)
	s_setprio 1
	s_waitcnt lgkmcnt(0)
	v_mfma_f32_16x16x32_bf16 v[158:161], v[34:37], v[50:53], 0
	v_mfma_f32_16x16x32_bf16 v[154:157], v[42:45], v[50:53], 0
	v_mfma_f32_16x16x32_bf16 v[142:145], v[34:37], v[62:65], 0
	v_mfma_f32_16x16x32_bf16 v[138:141], v[42:45], v[62:65], 0
	v_mfma_f32_16x16x32_bf16 v[126:129], v[34:37], v[170:173], 0
	v_mfma_f32_16x16x32_bf16 v[122:125], v[42:45], v[170:173], 0
	v_mfma_f32_16x16x32_bf16 v[110:113], v[34:37], v[178:181], 0
	v_mfma_f32_16x16x32_bf16 v[106:109], v[42:45], v[178:181], 0
	v_mfma_f32_16x16x32_bf16 v[158:161], v[38:41], v[58:61], v[158:161]
	v_mfma_f32_16x16x32_bf16 v[154:157], v[46:49], v[58:61], v[154:157]
	v_mfma_f32_16x16x32_bf16 v[142:145], v[38:41], v[66:69], v[142:145]
	v_mfma_f32_16x16x32_bf16 v[138:141], v[46:49], v[66:69], v[138:141]
	v_mfma_f32_16x16x32_bf16 v[126:129], v[38:41], v[174:177], v[126:129]
	v_mfma_f32_16x16x32_bf16 v[122:125], v[46:49], v[174:177], v[122:125]
	v_mfma_f32_16x16x32_bf16 v[110:113], v[38:41], v[182:185], v[110:113]
	v_mfma_f32_16x16x32_bf16 v[106:109], v[46:49], v[182:185], v[106:109]
	s_setprio 0
	s_barrier
	s_add_i32 s68, 0, 0x14000
	s_add_i32 s4, s67, s52
	v_add_u32_e32 v1, s68, v191
	v_lshl_add_u64 v[214:215], s[46:47], 0, v[164:165]
	s_mov_b32 m0, s4
	ds_read_b128 v[186:189], v1
	ds_read_b128 v[208:211], v1 offset:1024
	ds_read_b128 v[222:225], v1 offset:2048
	ds_read_b128 v[226:229], v1 offset:3072
	global_load_lds_dwordx4 v[214:215], off
	v_lshl_add_u64 v[238:239], s[46:47], 0, v[162:163]
	s_add_i32 m0, s4, 0x2000
	s_nop 0
	global_load_lds_dwordx4 v[238:239], off
	s_barrier
	s_waitcnt lgkmcnt(0)
	s_setprio 1
	s_waitcnt lgkmcnt(0)
	v_mfma_f32_16x16x32_bf16 v[150:153], v[186:189], v[50:53], 0
	v_mfma_f32_16x16x32_bf16 v[50:53], v[222:225], v[50:53], 0
	v_mfma_f32_16x16x32_bf16 v[150:153], v[208:211], v[58:61], v[150:153]
	v_mfma_f32_16x16x32_bf16 v[50:53], v[226:229], v[58:61], v[50:53]
	v_mfma_f32_16x16x32_bf16 v[58:61], v[186:189], v[62:65], 0
	v_mfma_f32_16x16x32_bf16 v[62:65], v[222:225], v[62:65], 0
	v_mfma_f32_16x16x32_bf16 v[114:117], v[222:225], v[170:173], 0
	v_mfma_f32_16x16x32_bf16 v[102:105], v[186:189], v[178:181], 0
	v_mfma_f32_16x16x32_bf16 v[98:101], v[222:225], v[178:181], 0
	v_mfma_f32_16x16x32_bf16 v[58:61], v[208:211], v[66:69], v[58:61]
	v_mfma_f32_16x16x32_bf16 v[62:65], v[226:229], v[66:69], v[62:65]
	v_mfma_f32_16x16x32_bf16 v[66:69], v[186:189], v[170:173], 0
	v_mfma_f32_16x16x32_bf16 v[114:117], v[226:229], v[174:177], v[114:117]
	v_mfma_f32_16x16x32_bf16 v[102:105], v[208:211], v[182:185], v[102:105]
	v_mfma_f32_16x16x32_bf16 v[98:101], v[226:229], v[182:185], v[98:101]
	v_mfma_f32_16x16x32_bf16 v[66:69], v[208:211], v[174:177], v[66:69]
	s_setprio 0
	s_mov_b32 m0, s53
	v_lshl_add_u64 v[240:241], s[48:49], 0, v[164:165]
	s_barrier
	ds_read_b128 v[118:121], v206 offset:16384
	ds_read_b128 v[130:133], v206 offset:17408
	ds_read_b128 v[134:137], v206 offset:18432
	ds_read_b128 v[146:149], v206 offset:19456
	ds_read_b128 v[170:173], v206 offset:20480
	ds_read_b128 v[174:177], v206 offset:21504
	ds_read_b128 v[178:181], v206 offset:22528
	ds_read_b128 v[182:185], v206 offset:23552
	global_load_lds_dwordx4 v[240:241], off
	v_lshl_add_u64 v[242:243], s[48:49], 0, v[162:163]
	s_mov_b32 m0, s54
	s_nop 0
	global_load_lds_dwordx4 v[242:243], off
	s_barrier
	s_waitcnt lgkmcnt(0)
	s_setprio 1
	s_waitcnt lgkmcnt(0)
	v_mfma_f32_16x16x32_bf16 v[94:97], v[34:37], v[118:121], 0
	v_mfma_f32_16x16x32_bf16 v[90:93], v[42:45], v[118:121], 0
	v_mfma_f32_16x16x32_bf16 v[78:81], v[34:37], v[134:137], 0
	v_mfma_f32_16x16x32_bf16 v[74:77], v[42:45], v[134:137], 0
	v_mfma_f32_16x16x32_bf16 v[30:33], v[34:37], v[170:173], 0
	v_mfma_f32_16x16x32_bf16 v[26:29], v[42:45], v[170:173], 0
	v_mfma_f32_16x16x32_bf16 v[14:17], v[34:37], v[178:181], 0
	v_mfma_f32_16x16x32_bf16 v[10:13], v[42:45], v[178:181], 0
	v_mfma_f32_16x16x32_bf16 v[94:97], v[38:41], v[130:133], v[94:97]
	v_mfma_f32_16x16x32_bf16 v[90:93], v[46:49], v[130:133], v[90:93]
	v_mfma_f32_16x16x32_bf16 v[78:81], v[38:41], v[146:149], v[78:81]
	v_mfma_f32_16x16x32_bf16 v[74:77], v[46:49], v[146:149], v[74:77]
	v_mfma_f32_16x16x32_bf16 v[30:33], v[38:41], v[174:177], v[30:33]
	v_mfma_f32_16x16x32_bf16 v[26:29], v[46:49], v[174:177], v[26:29]
	v_mfma_f32_16x16x32_bf16 v[14:17], v[38:41], v[182:185], v[14:17]
	v_mfma_f32_16x16x32_bf16 v[10:13], v[46:49], v[182:185], v[10:13]
	s_setprio 0
	s_barrier
	s_add_u32 s4, s46, 0x40000
	s_addc_u32 s5, s47, 0
	s_add_i32 s67, s68, s52
	v_lshl_add_u64 v[34:35], s[4:5], 0, v[164:165]
	s_mov_b32 m0, s67
	s_nop 0
	global_load_lds_dwordx4 v[34:35], off
	v_lshl_add_u64 v[34:35], s[4:5], 0, v[162:163]
	s_add_i32 m0, s67, 0x2000
	s_nop 0
	global_load_lds_dwordx4 v[34:35], off
	s_waitcnt vmcnt(6)
	s_barrier
	s_setprio 1
	v_mfma_f32_16x16x32_bf16 v[22:25], v[186:189], v[170:173], 0
	v_mfma_f32_16x16x32_bf16 v[18:21], v[222:225], v[170:173], 0
	v_mfma_f32_16x16x32_bf16 v[6:9], v[186:189], v[178:181], 0
	v_mfma_f32_16x16x32_bf16 v[2:5], v[222:225], v[178:181], 0
	v_mfma_f32_16x16x32_bf16 v[34:37], v[186:189], v[118:121], 0
	v_mfma_f32_16x16x32_bf16 v[38:41], v[222:225], v[118:121], 0
	v_mfma_f32_16x16x32_bf16 v[42:45], v[186:189], v[134:137], 0
	v_mfma_f32_16x16x32_bf16 v[46:49], v[222:225], v[134:137], 0
	v_mfma_f32_16x16x32_bf16 v[22:25], v[208:211], v[174:177], v[22:25]
	v_mfma_f32_16x16x32_bf16 v[18:21], v[226:229], v[174:177], v[18:21]
	v_mfma_f32_16x16x32_bf16 v[6:9], v[208:211], v[182:185], v[6:9]
	v_mfma_f32_16x16x32_bf16 v[2:5], v[226:229], v[182:185], v[2:5]
	v_mfma_f32_16x16x32_bf16 v[34:37], v[208:211], v[130:133], v[34:37]
	v_mfma_f32_16x16x32_bf16 v[38:41], v[226:229], v[130:133], v[38:41]
	v_mfma_f32_16x16x32_bf16 v[42:45], v[208:211], v[146:149], v[42:45]
	v_mfma_f32_16x16x32_bf16 v[46:49], v[226:229], v[146:149], v[46:49]
	s_setprio 0
	s_add_i32 s67, 0, 0x18000
	v_add_u32_e32 v1, s67, v191
	s_barrier
	ds_read_b128 v[54:57], v1
	ds_read_b128 v[70:73], v1 offset:1024
	ds_read_b128 v[82:85], v1 offset:2048
	ds_read_b128 v[86:89], v1 offset:3072
	s_add_u32 s4, s48, 0x40000
	s_addc_u32 s5, s49, 0
	s_mov_b32 m0, s55
	v_lshl_add_u64 v[134:135], s[4:5], 0, v[164:165]
	ds_read_b128 v[118:121], v206 offset:32768
	ds_read_b128 v[130:133], v206 offset:33792
	ds_read_b128 v[170:173], v206 offset:34816
	ds_read_b128 v[174:177], v206 offset:35840
	ds_read_b128 v[178:181], v206 offset:36864
	ds_read_b128 v[182:185], v206 offset:37888
	ds_read_b128 v[186:189], v206 offset:38912
	ds_read_b128 v[208:211], v206 offset:39936
	global_load_lds_dwordx4 v[134:135], off
	v_lshl_add_u64 v[134:135], s[4:5], 0, v[162:163]
	s_mov_b32 m0, s56
	s_nop 0
	global_load_lds_dwordx4 v[134:135], off
	s_waitcnt lgkmcnt(8)
	s_barrier
	s_waitcnt lgkmcnt(0)
	s_setprio 1
	s_waitcnt lgkmcnt(0)
	v_mfma_f32_16x16x32_bf16 v[134:137], v[54:57], v[118:121], v[158:161]
	v_mfma_f32_16x16x32_bf16 v[158:161], v[70:73], v[130:133], v[134:137]
	v_mfma_f32_16x16x32_bf16 v[134:137], v[82:85], v[118:121], v[154:157]
	v_mfma_f32_16x16x32_bf16 v[154:157], v[86:89], v[130:133], v[134:137]
	v_mfma_f32_16x16x32_bf16 v[134:137], v[54:57], v[170:173], v[142:145]
	v_mfma_f32_16x16x32_bf16 v[142:145], v[70:73], v[174:177], v[134:137]
	v_mfma_f32_16x16x32_bf16 v[134:137], v[82:85], v[170:173], v[138:141]
	v_mfma_f32_16x16x32_bf16 v[126:129], v[54:57], v[178:181], v[126:129]
	v_mfma_f32_16x16x32_bf16 v[122:125], v[82:85], v[178:181], v[122:125]
	v_mfma_f32_16x16x32_bf16 v[110:113], v[54:57], v[186:189], v[110:113]
	v_mfma_f32_16x16x32_bf16 v[106:109], v[82:85], v[186:189], v[106:109]
	v_mfma_f32_16x16x32_bf16 v[138:141], v[86:89], v[174:177], v[134:137]
	v_mfma_f32_16x16x32_bf16 v[126:129], v[70:73], v[182:185], v[126:129]
	v_mfma_f32_16x16x32_bf16 v[122:125], v[86:89], v[182:185], v[122:125]
	v_mfma_f32_16x16x32_bf16 v[110:113], v[70:73], v[208:211], v[110:113]
	v_mfma_f32_16x16x32_bf16 v[106:109], v[86:89], v[208:211], v[106:109]
	s_setprio 0
	s_barrier
	s_add_i32 s48, 0, 0x1c000
	s_add_i32 s4, s67, s52
	v_add_u32_e32 v1, s48, v191
	v_lshl_add_u64 v[134:135], v[214:215], 0, s[22:23]
	s_mov_b32 m0, s4
	ds_read_b128 v[222:225], v1
	ds_read_b128 v[226:229], v1 offset:1024
	ds_read_b128 v[230:233], v1 offset:2048
	ds_read_b128 v[234:237], v1 offset:3072
	global_load_lds_dwordx4 v[134:135], off
	v_lshl_add_u64 v[134:135], v[238:239], 0, s[22:23]
	s_add_i32 m0, s4, 0x2000
	s_nop 0
	global_load_lds_dwordx4 v[134:135], off
	s_barrier
	s_waitcnt lgkmcnt(0)
	s_setprio 1
	s_waitcnt lgkmcnt(0)
	v_mfma_f32_16x16x32_bf16 v[50:53], v[230:233], v[118:121], v[50:53]
	v_mfma_f32_16x16x32_bf16 v[134:137], v[222:225], v[118:121], v[150:153]
	v_mfma_f32_16x16x32_bf16 v[146:149], v[234:237], v[130:133], v[50:53]
	v_mfma_f32_16x16x32_bf16 v[50:53], v[222:225], v[170:173], v[58:61]
	v_mfma_f32_16x16x32_bf16 v[150:153], v[226:229], v[130:133], v[134:137]
	v_mfma_f32_16x16x32_bf16 v[134:137], v[226:229], v[174:177], v[50:53]
	v_mfma_f32_16x16x32_bf16 v[50:53], v[230:233], v[170:173], v[62:65]
	v_mfma_f32_16x16x32_bf16 v[130:133], v[234:237], v[174:177], v[50:53]
	v_mfma_f32_16x16x32_bf16 v[50:53], v[222:225], v[178:181], v[66:69]
	v_mfma_f32_16x16x32_bf16 v[118:121], v[226:229], v[182:185], v[50:53]
	v_mfma_f32_16x16x32_bf16 v[50:53], v[230:233], v[178:181], v[114:117]
	v_mfma_f32_16x16x32_bf16 v[114:117], v[234:237], v[182:185], v[50:53]
	v_mfma_f32_16x16x32_bf16 v[50:53], v[222:225], v[186:189], v[102:105]
	v_mfma_f32_16x16x32_bf16 v[102:105], v[226:229], v[208:211], v[50:53]
	v_mfma_f32_16x16x32_bf16 v[50:53], v[230:233], v[186:189], v[98:101]
	v_mfma_f32_16x16x32_bf16 v[98:101], v[234:237], v[208:211], v[50:53]
	s_setprio 0
	s_mov_b32 m0, s58
	v_lshl_add_u64 v[186:187], v[240:241], 0, s[22:23]
	s_barrier
	s_nop 2
	ds_read_b128 v[50:53], v206 offset:49152
	ds_read_b128 v[58:61], v206 offset:50176
	ds_read_b128 v[62:65], v206 offset:51200
	ds_read_b128 v[66:69], v206 offset:52224
	ds_read_b128 v[170:173], v206 offset:53248
	ds_read_b128 v[174:177], v206 offset:54272
	ds_read_b128 v[178:181], v206 offset:55296
	ds_read_b128 v[182:185], v206 offset:56320
	global_load_lds_dwordx4 v[186:187], off
	v_lshl_add_u64 v[186:187], v[242:243], 0, s[22:23]
	s_mov_b32 m0, s59
	s_nop 0
	global_load_lds_dwordx4 v[186:187], off
	s_barrier
	s_waitcnt lgkmcnt(0)
	s_setprio 1
	s_waitcnt lgkmcnt(0)
	v_mfma_f32_16x16x32_bf16 v[94:97], v[54:57], v[50:53], v[94:97]
	v_mfma_f32_16x16x32_bf16 v[90:93], v[82:85], v[50:53], v[90:93]
	v_mfma_f32_16x16x32_bf16 v[78:81], v[54:57], v[62:65], v[78:81]
	v_mfma_f32_16x16x32_bf16 v[74:77], v[82:85], v[62:65], v[74:77]
	v_mfma_f32_16x16x32_bf16 v[30:33], v[54:57], v[170:173], v[30:33]
	v_mfma_f32_16x16x32_bf16 v[26:29], v[82:85], v[170:173], v[26:29]
	v_mfma_f32_16x16x32_bf16 v[14:17], v[54:57], v[178:181], v[14:17]
	v_mfma_f32_16x16x32_bf16 v[10:13], v[82:85], v[178:181], v[10:13]
	v_mfma_f32_16x16x32_bf16 v[94:97], v[70:73], v[58:61], v[94:97]
	v_mfma_f32_16x16x32_bf16 v[90:93], v[86:89], v[58:61], v[90:93]
	v_mfma_f32_16x16x32_bf16 v[78:81], v[70:73], v[66:69], v[78:81]
	v_mfma_f32_16x16x32_bf16 v[74:77], v[86:89], v[66:69], v[74:77]
	v_mfma_f32_16x16x32_bf16 v[30:33], v[70:73], v[174:177], v[30:33]
	v_mfma_f32_16x16x32_bf16 v[26:29], v[86:89], v[174:177], v[26:29]
	v_mfma_f32_16x16x32_bf16 v[14:17], v[70:73], v[182:185], v[14:17]
	v_mfma_f32_16x16x32_bf16 v[10:13], v[86:89], v[182:185], v[10:13]
	s_setprio 0
	s_barrier
	s_add_u32 s4, s46, 0x40080
	s_addc_u32 s5, s47, 0
	s_add_i32 s46, s48, s52
	v_lshl_add_u64 v[54:55], s[4:5], 0, v[164:165]
	s_mov_b32 m0, s46
	s_nop 0
	global_load_lds_dwordx4 v[54:55], off
	v_lshl_add_u64 v[54:55], s[4:5], 0, v[162:163]
	s_add_i32 m0, s46, 0x2000
	s_nop 0
	global_load_lds_dwordx4 v[54:55], off
	s_waitcnt vmcnt(6)
	s_barrier
	s_setprio 1
	v_mfma_f32_16x16x32_bf16 v[34:37], v[222:225], v[50:53], v[34:37]
	v_mfma_f32_16x16x32_bf16 v[86:89], v[226:229], v[58:61], v[34:37]
	v_mfma_f32_16x16x32_bf16 v[34:37], v[230:233], v[50:53], v[38:41]
	v_mfma_f32_16x16x32_bf16 v[82:85], v[234:237], v[58:61], v[34:37]
	v_mfma_f32_16x16x32_bf16 v[34:37], v[222:225], v[62:65], v[42:45]
	v_mfma_f32_16x16x32_bf16 v[70:73], v[226:229], v[66:69], v[34:37]
	v_mfma_f32_16x16x32_bf16 v[34:37], v[230:233], v[62:65], v[46:49]
	v_mfma_f32_16x16x32_bf16 v[22:25], v[222:225], v[170:173], v[22:25]
	v_mfma_f32_16x16x32_bf16 v[18:21], v[230:233], v[170:173], v[18:21]
	v_mfma_f32_16x16x32_bf16 v[6:9], v[222:225], v[178:181], v[6:9]
	v_mfma_f32_16x16x32_bf16 v[2:5], v[230:233], v[178:181], v[2:5]
	v_mfma_f32_16x16x32_bf16 v[54:57], v[234:237], v[66:69], v[34:37]
	v_mfma_f32_16x16x32_bf16 v[22:25], v[226:229], v[174:177], v[22:25]
	v_mfma_f32_16x16x32_bf16 v[18:21], v[234:237], v[174:177], v[18:21]
	v_mfma_f32_16x16x32_bf16 v[6:9], v[226:229], v[182:185], v[6:9]
	v_mfma_f32_16x16x32_bf16 v[2:5], v[234:237], v[182:185], v[2:5]
	s_setprio 0
	s_add_i32 s66, s66, 2
	s_add_u32 s64, s64, 0x100
	s_addc_u32 s65, s65, 0
	s_cmp_gt_u32 s66, 13
	s_mov_b64 s[4:5], s[36:37]
	s_barrier

.LBB0_395:
	s_add_i32 s66, s66, 1
	s_mov_b64 s[36:37], s[20:21]
	s_mul_i32 s20, s66, s26
	s_add_i32 s42, s20, s2
	s_cmpk_gt_i32 s42, 0x3ff
	s_cselect_b64 s[52:53], -1, 0
	s_lshl_b32 s20, s42, 3
	s_and_b32 s20, s20, 56
	s_bfe_u32 s21, s42, 0x30003
	s_mov_b32 s3, s67
	s_or_b32 s67, s20, s21
	s_mov_b32 s27, s50
	s_ashr_i32 s50, s42, 6
	s_lshl_b32 s20, s67, 19
	s_mov_b64 s[4:5], s[48:49]
	s_add_u32 s48, s18, s20
	s_addc_u32 s49, s19, 0
	s_ashr_i32 s51, s50, 31
	s_lshl_b64 s[20:21], s[50:51], 19
	s_add_u32 s20, s16, s20
	s_addc_u32 s21, s17, s21
	s_cmpk_lt_i32 s42, 0x400
	s_cselect_b32 s46, s49, s5
	s_cselect_b32 s47, s48, s4
	s_cselect_b32 s51, s21, s37
	s_cselect_b32 s54, s20, s36
	s_add_u32 s55, s36, 0x100
	s_addc_u32 s56, s37, 0
	s_mov_b32 s57, -2
	s_add_u32 s36, s4, 0x100
	s_addc_u32 s37, s5, 0
	s_add_i32 s68, 0, 0x10000
	v_add_u32_e32 v30, s68, v204
	ds_read_b128 v[14:17], v30
	ds_read_b128 v[22:25], v30 offset:1024
	ds_read_b128 v[26:29], v30 offset:2048
	ds_read_b128 v[30:33], v30 offset:3072
	s_cmp_eq_u32 s57, 12
	s_cselect_b32 s45, s46, s37
	s_cselect_b32 s44, s47, s36
	s_cselect_b32 s43, s51, s56
	s_cselect_b32 s42, s54, s55
	v_lshl_add_u64 v[178:179], s[4:5], 0, v[188:189]
	s_add_i32 m0, s60, 0xc000
	ds_read_b128 v[38:41], v209
	ds_read_b128 v[42:45], v209 offset:1024
	ds_read_b128 v[46:49], v209 offset:2048
	ds_read_b128 v[54:57], v209 offset:3072
	ds_read_b128 v[58:61], v209 offset:4096
	ds_read_b128 v[62:65], v209 offset:5120
	ds_read_b128 v[66:69], v209 offset:6144
	ds_read_b128 v[70:73], v209 offset:7168
	global_load_lds_dwordx4 v[178:179], off
	v_lshl_add_u64 v[178:179], s[4:5], 0, v[186:187]
	s_add_i32 m0, s60, 0xe000
	s_nop 0
	global_load_lds_dwordx4 v[178:179], off
	s_waitcnt lgkmcnt(8)
	s_barrier
	s_waitcnt lgkmcnt(0)
	s_setprio 1
	s_waitcnt lgkmcnt(0)
	v_mfma_f32_16x16x32_bf16 v[174:177], v[14:17], v[38:41], 0
	v_mfma_f32_16x16x32_bf16 v[170:173], v[26:29], v[38:41], 0
	v_mfma_f32_16x16x32_bf16 v[158:161], v[14:17], v[46:49], 0
	v_mfma_f32_16x16x32_bf16 v[154:157], v[26:29], v[46:49], 0
	v_mfma_f32_16x16x32_bf16 v[142:145], v[14:17], v[58:61], 0
	v_mfma_f32_16x16x32_bf16 v[138:141], v[26:29], v[58:61], 0
	v_mfma_f32_16x16x32_bf16 v[126:129], v[14:17], v[66:69], 0
	v_mfma_f32_16x16x32_bf16 v[122:125], v[26:29], v[66:69], 0
	v_mfma_f32_16x16x32_bf16 v[174:177], v[22:25], v[42:45], v[174:177]
	v_mfma_f32_16x16x32_bf16 v[170:173], v[30:33], v[42:45], v[170:173]
	v_mfma_f32_16x16x32_bf16 v[158:161], v[22:25], v[54:57], v[158:161]
	v_mfma_f32_16x16x32_bf16 v[154:157], v[30:33], v[54:57], v[154:157]
	v_mfma_f32_16x16x32_bf16 v[142:145], v[22:25], v[62:65], v[142:145]
	v_mfma_f32_16x16x32_bf16 v[138:141], v[30:33], v[62:65], v[138:141]
	v_mfma_f32_16x16x32_bf16 v[126:129], v[22:25], v[70:73], v[126:129]
	v_mfma_f32_16x16x32_bf16 v[122:125], v[30:33], v[70:73], v[122:125]
	s_setprio 0
	s_barrier
	s_add_i32 s69, 0, 0x14000
	v_add_u32_e32 v210, s69, v204
	s_add_i32 s4, s68, s59
	ds_read_b128 v[178:181], v210
	ds_read_b128 v[190:193], v210 offset:1024
	ds_read_b128 v[200:203], v210 offset:2048
	ds_read_b128 v[222:225], v210 offset:3072
	v_lshl_add_u64 v[210:211], s[42:43], 0, v[184:185]
	s_mov_b32 m0, s4
	v_lshl_add_u64 v[214:215], s[42:43], 0, v[182:183]
	global_load_lds_dwordx4 v[210:211], off
	s_add_i32 m0, s4, 0x2000
	s_nop 0
	global_load_lds_dwordx4 v[214:215], off
	s_barrier
	s_waitcnt lgkmcnt(0)
	s_setprio 1
	s_waitcnt lgkmcnt(0)
	v_mfma_f32_16x16x32_bf16 v[166:169], v[178:181], v[38:41], 0
	v_mfma_f32_16x16x32_bf16 v[38:41], v[200:203], v[38:41], 0
	v_mfma_f32_16x16x32_bf16 v[166:169], v[190:193], v[42:45], v[166:169]
	v_mfma_f32_16x16x32_bf16 v[38:41], v[222:225], v[42:45], v[38:41]
	v_mfma_f32_16x16x32_bf16 v[42:45], v[178:181], v[46:49], 0
	v_mfma_f32_16x16x32_bf16 v[46:49], v[200:203], v[46:49], 0
	v_mfma_f32_16x16x32_bf16 v[42:45], v[190:193], v[54:57], v[42:45]
	v_mfma_f32_16x16x32_bf16 v[46:49], v[222:225], v[54:57], v[46:49]
	v_mfma_f32_16x16x32_bf16 v[54:57], v[178:181], v[58:61], 0
	v_mfma_f32_16x16x32_bf16 v[58:61], v[200:203], v[58:61], 0
	v_mfma_f32_16x16x32_bf16 v[54:57], v[190:193], v[62:65], v[54:57]
	v_mfma_f32_16x16x32_bf16 v[58:61], v[222:225], v[62:65], v[58:61]
	v_mfma_f32_16x16x32_bf16 v[62:65], v[178:181], v[66:69], 0
	v_mfma_f32_16x16x32_bf16 v[66:69], v[200:203], v[66:69], 0
	v_mfma_f32_16x16x32_bf16 v[62:65], v[190:193], v[70:73], v[62:65]
	v_mfma_f32_16x16x32_bf16 v[66:69], v[222:225], v[70:73], v[66:69]
	s_setprio 0
	s_mov_b32 m0, s60
	v_lshl_add_u64 v[242:243], s[44:45], 0, v[184:185]
	s_barrier
	ds_read_b128 v[70:73], v209 offset:16384
	ds_read_b128 v[114:117], v209 offset:17408
	ds_read_b128 v[118:121], v209 offset:18432
	ds_read_b128 v[130:133], v209 offset:19456
	ds_read_b128 v[134:137], v209 offset:20480
	ds_read_b128 v[146:149], v209 offset:21504
	ds_read_b128 v[150:153], v209 offset:22528
	ds_read_b128 v[162:165], v209 offset:23552
	global_load_lds_dwordx4 v[242:243], off
	v_lshl_add_u64 v[244:245], s[44:45], 0, v[182:183]
	s_mov_b32 m0, s61
	s_nop 0
	global_load_lds_dwordx4 v[244:245], off
	s_barrier
	s_waitcnt lgkmcnt(0)
	s_setprio 1
	s_waitcnt lgkmcnt(0)
	v_mfma_f32_16x16x32_bf16 v[110:113], v[14:17], v[70:73], 0
	v_mfma_f32_16x16x32_bf16 v[106:109], v[26:29], v[70:73], 0
	v_mfma_f32_16x16x32_bf16 v[94:97], v[14:17], v[118:121], 0
	v_mfma_f32_16x16x32_bf16 v[90:93], v[26:29], v[118:121], 0
	v_mfma_f32_16x16x32_bf16 v[78:81], v[14:17], v[134:137], 0
	v_mfma_f32_16x16x32_bf16 v[74:77], v[26:29], v[134:137], 0
	v_mfma_f32_16x16x32_bf16 v[10:13], v[26:29], v[150:153], 0
	v_mfma_f32_16x16x32_bf16 v[110:113], v[22:25], v[114:117], v[110:113]
	v_mfma_f32_16x16x32_bf16 v[106:109], v[30:33], v[114:117], v[106:109]
	v_mfma_f32_16x16x32_bf16 v[94:97], v[22:25], v[130:133], v[94:97]
	v_mfma_f32_16x16x32_bf16 v[90:93], v[30:33], v[130:133], v[90:93]
	v_mfma_f32_16x16x32_bf16 v[78:81], v[22:25], v[146:149], v[78:81]
	v_mfma_f32_16x16x32_bf16 v[74:77], v[30:33], v[146:149], v[74:77]
	v_mfma_f32_16x16x32_bf16 v[14:17], v[14:17], v[150:153], 0
	v_mfma_f32_16x16x32_bf16 v[10:13], v[30:33], v[162:165], v[10:13]
	v_mfma_f32_16x16x32_bf16 v[14:17], v[22:25], v[162:165], v[14:17]
	s_setprio 0
	s_barrier
	s_add_u32 s4, s42, 0x40000
	s_addc_u32 s5, s43, 0
	s_add_i32 s68, s69, s59
	v_lshl_add_u64 v[18:19], s[4:5], 0, v[184:185]
	s_mov_b32 m0, s68
	s_nop 0
	global_load_lds_dwordx4 v[18:19], off
	v_lshl_add_u64 v[18:19], s[4:5], 0, v[182:183]
	s_add_i32 m0, s68, 0x2000
	s_nop 0
	global_load_lds_dwordx4 v[18:19], off
	s_waitcnt vmcnt(6)
	s_barrier
	s_setprio 1
	v_mfma_f32_16x16x32_bf16 v[18:21], v[178:181], v[70:73], 0
	v_mfma_f32_16x16x32_bf16 v[22:25], v[190:193], v[114:117], v[18:21]
	v_mfma_f32_16x16x32_bf16 v[18:21], v[200:203], v[70:73], 0
	v_mfma_f32_16x16x32_bf16 v[26:29], v[222:225], v[114:117], v[18:21]
	v_mfma_f32_16x16x32_bf16 v[18:21], v[178:181], v[118:121], 0
	v_mfma_f32_16x16x32_bf16 v[30:33], v[190:193], v[130:133], v[18:21]
	v_mfma_f32_16x16x32_bf16 v[18:21], v[200:203], v[118:121], 0
	v_mfma_f32_16x16x32_bf16 v[70:73], v[222:225], v[130:133], v[18:21]
	v_mfma_f32_16x16x32_bf16 v[18:21], v[178:181], v[134:137], 0
	v_mfma_f32_16x16x32_bf16 v[50:53], v[190:193], v[146:149], v[18:21]
	v_mfma_f32_16x16x32_bf16 v[18:21], v[200:203], v[134:137], 0
	v_mfma_f32_16x16x32_bf16 v[6:9], v[178:181], v[150:153], 0
	v_mfma_f32_16x16x32_bf16 v[2:5], v[200:203], v[150:153], 0
	v_mfma_f32_16x16x32_bf16 v[34:37], v[222:225], v[146:149], v[18:21]
	v_mfma_f32_16x16x32_bf16 v[6:9], v[190:193], v[162:165], v[6:9]
	v_mfma_f32_16x16x32_bf16 v[2:5], v[222:225], v[162:165], v[2:5]
	s_setprio 0
	s_add_i32 s68, 0, 0x18000
	v_add_u32_e32 v98, s68, v204
	s_barrier
	ds_read_b128 v[18:21], v98
	ds_read_b128 v[82:85], v98 offset:1024
	ds_read_b128 v[86:89], v98 offset:2048
	ds_read_b128 v[98:101], v98 offset:3072
	s_add_u32 s4, s44, 0x40000
	s_addc_u32 s5, s45, 0
	s_mov_b32 m0, s62
	v_lshl_add_u64 v[134:135], s[4:5], 0, v[184:185]
	ds_read_b128 v[102:105], v209 offset:32768
	ds_read_b128 v[114:117], v209 offset:33792
	ds_read_b128 v[118:121], v209 offset:34816
	ds_read_b128 v[130:133], v209 offset:35840
	ds_read_b128 v[178:181], v209 offset:36864
	ds_read_b128 v[190:193], v209 offset:37888
	ds_read_b128 v[200:203], v209 offset:38912
	ds_read_b128 v[222:225], v209 offset:39936
	global_load_lds_dwordx4 v[134:135], off
	v_lshl_add_u64 v[134:135], s[4:5], 0, v[182:183]
	s_mov_b32 m0, s63
	s_nop 0
	global_load_lds_dwordx4 v[134:135], off
	s_waitcnt lgkmcnt(8)
	s_barrier
	s_waitcnt lgkmcnt(0)
	s_setprio 1
	s_waitcnt lgkmcnt(0)
	v_mfma_f32_16x16x32_bf16 v[134:137], v[18:21], v[102:105], v[174:177]
	v_mfma_f32_16x16x32_bf16 v[174:177], v[82:85], v[114:117], v[134:137]
	v_mfma_f32_16x16x32_bf16 v[134:137], v[86:89], v[102:105], v[170:173]
	v_mfma_f32_16x16x32_bf16 v[170:173], v[98:101], v[114:117], v[134:137]
	v_mfma_f32_16x16x32_bf16 v[134:137], v[18:21], v[118:121], v[158:161]
	v_mfma_f32_16x16x32_bf16 v[158:161], v[82:85], v[130:133], v[134:137]
	v_mfma_f32_16x16x32_bf16 v[134:137], v[86:89], v[118:121], v[154:157]
	v_mfma_f32_16x16x32_bf16 v[154:157], v[98:101], v[130:133], v[134:137]
	v_mfma_f32_16x16x32_bf16 v[134:137], v[18:21], v[178:181], v[142:145]
	v_mfma_f32_16x16x32_bf16 v[142:145], v[82:85], v[190:193], v[134:137]
	v_mfma_f32_16x16x32_bf16 v[134:137], v[86:89], v[178:181], v[138:141]
	v_mfma_f32_16x16x32_bf16 v[126:129], v[18:21], v[200:203], v[126:129]
	v_mfma_f32_16x16x32_bf16 v[122:125], v[86:89], v[200:203], v[122:125]
	v_mfma_f32_16x16x32_bf16 v[138:141], v[98:101], v[190:193], v[134:137]
	v_mfma_f32_16x16x32_bf16 v[126:129], v[82:85], v[222:225], v[126:129]
	v_mfma_f32_16x16x32_bf16 v[122:125], v[98:101], v[222:225], v[122:125]
	s_setprio 0
	s_barrier
	s_add_i32 s44, 0, 0x1c000
	v_add_u32_e32 v134, s44, v204
	s_add_i32 s4, s68, s59
	ds_read_b128 v[226:229], v134
	ds_read_b128 v[230:233], v134 offset:1024
	ds_read_b128 v[234:237], v134 offset:2048
	ds_read_b128 v[238:241], v134 offset:3072
	v_lshl_add_u64 v[134:135], v[210:211], 0, s[22:23]
	s_mov_b32 m0, s4
	s_nop 0
	global_load_lds_dwordx4 v[134:135], off
	v_lshl_add_u64 v[134:135], v[214:215], 0, s[22:23]
	s_add_i32 m0, s4, 0x2000
	s_nop 0
	global_load_lds_dwordx4 v[134:135], off
	s_barrier
	s_waitcnt lgkmcnt(0)
	s_setprio 1
	s_waitcnt lgkmcnt(0)
	v_mfma_f32_16x16x32_bf16 v[38:41], v[234:237], v[102:105], v[38:41]
	v_mfma_f32_16x16x32_bf16 v[162:165], v[238:241], v[114:117], v[38:41]
	v_mfma_f32_16x16x32_bf16 v[38:41], v[226:229], v[118:121], v[42:45]
	v_mfma_f32_16x16x32_bf16 v[150:153], v[230:233], v[130:133], v[38:41]
	v_mfma_f32_16x16x32_bf16 v[38:41], v[234:237], v[118:121], v[46:49]
	v_mfma_f32_16x16x32_bf16 v[134:137], v[226:229], v[102:105], v[166:169]
	v_mfma_f32_16x16x32_bf16 v[146:149], v[238:241], v[130:133], v[38:41]
	v_mfma_f32_16x16x32_bf16 v[38:41], v[226:229], v[178:181], v[54:57]
	v_mfma_f32_16x16x32_bf16 v[166:169], v[230:233], v[114:117], v[134:137]
	v_mfma_f32_16x16x32_bf16 v[134:137], v[230:233], v[190:193], v[38:41]
	v_mfma_f32_16x16x32_bf16 v[38:41], v[234:237], v[178:181], v[58:61]
	v_mfma_f32_16x16x32_bf16 v[130:133], v[238:241], v[190:193], v[38:41]
	v_mfma_f32_16x16x32_bf16 v[38:41], v[226:229], v[200:203], v[62:65]
	v_mfma_f32_16x16x32_bf16 v[118:121], v[230:233], v[222:225], v[38:41]
	v_mfma_f32_16x16x32_bf16 v[38:41], v[234:237], v[200:203], v[66:69]
	v_mfma_f32_16x16x32_bf16 v[114:117], v[238:241], v[222:225], v[38:41]
	s_setprio 0
	s_mov_b32 m0, s64
	v_lshl_add_u64 v[102:103], v[242:243], 0, s[22:23]
	s_barrier
	s_nop 2
	ds_read_b128 v[38:41], v209 offset:49152
	ds_read_b128 v[42:45], v209 offset:50176
	ds_read_b128 v[46:49], v209 offset:51200
	ds_read_b128 v[54:57], v209 offset:52224
	ds_read_b128 v[58:61], v209 offset:53248
	ds_read_b128 v[62:65], v209 offset:54272
	ds_read_b128 v[66:69], v209 offset:55296
	ds_read_b128 v[178:181], v209 offset:56320
	global_load_lds_dwordx4 v[102:103], off
	v_lshl_add_u64 v[102:103], v[244:245], 0, s[22:23]
	s_mov_b32 m0, s65
	s_nop 0
	global_load_lds_dwordx4 v[102:103], off
	s_barrier
	s_waitcnt lgkmcnt(0)
	s_setprio 1
	s_waitcnt lgkmcnt(0)
	v_mfma_f32_16x16x32_bf16 v[102:105], v[18:21], v[38:41], v[110:113]
	v_mfma_f32_16x16x32_bf16 v[110:113], v[82:85], v[42:45], v[102:105]
	v_mfma_f32_16x16x32_bf16 v[102:105], v[86:89], v[38:41], v[106:109]
	v_mfma_f32_16x16x32_bf16 v[94:97], v[18:21], v[46:49], v[94:97]
	v_mfma_f32_16x16x32_bf16 v[90:93], v[86:89], v[46:49], v[90:93]
	v_mfma_f32_16x16x32_bf16 v[78:81], v[18:21], v[58:61], v[78:81]
	v_mfma_f32_16x16x32_bf16 v[74:77], v[86:89], v[58:61], v[74:77]
	v_mfma_f32_16x16x32_bf16 v[14:17], v[18:21], v[66:69], v[14:17]
	v_mfma_f32_16x16x32_bf16 v[10:13], v[86:89], v[66:69], v[10:13]
	v_mfma_f32_16x16x32_bf16 v[106:109], v[98:101], v[42:45], v[102:105]
	v_mfma_f32_16x16x32_bf16 v[94:97], v[82:85], v[54:57], v[94:97]
	v_mfma_f32_16x16x32_bf16 v[90:93], v[98:101], v[54:57], v[90:93]
	v_mfma_f32_16x16x32_bf16 v[78:81], v[82:85], v[62:65], v[78:81]
	v_mfma_f32_16x16x32_bf16 v[74:77], v[98:101], v[62:65], v[74:77]
	v_mfma_f32_16x16x32_bf16 v[18:21], v[82:85], v[178:181], v[14:17]
	v_mfma_f32_16x16x32_bf16 v[10:13], v[98:101], v[178:181], v[10:13]
	s_setprio 0
	s_barrier
	s_add_u32 s4, s42, 0x40080
	s_addc_u32 s5, s43, 0
	s_add_i32 s42, s44, s59
	v_lshl_add_u64 v[14:15], s[4:5], 0, v[184:185]
	s_mov_b32 m0, s42
	s_nop 0
	global_load_lds_dwordx4 v[14:15], off
	v_lshl_add_u64 v[14:15], s[4:5], 0, v[182:183]
	s_add_i32 m0, s42, 0x2000
	s_nop 0
	global_load_lds_dwordx4 v[14:15], off
	s_waitcnt vmcnt(6)
	s_barrier
	s_setprio 1
	v_mfma_f32_16x16x32_bf16 v[14:17], v[226:229], v[38:41], v[22:25]
	v_mfma_f32_16x16x32_bf16 v[102:105], v[230:233], v[42:45], v[14:17]
	v_mfma_f32_16x16x32_bf16 v[14:17], v[234:237], v[38:41], v[26:29]
	v_mfma_f32_16x16x32_bf16 v[98:101], v[238:241], v[42:45], v[14:17]
	v_mfma_f32_16x16x32_bf16 v[14:17], v[226:229], v[46:49], v[30:33]
	v_mfma_f32_16x16x32_bf16 v[86:89], v[230:233], v[54:57], v[14:17]
	v_mfma_f32_16x16x32_bf16 v[14:17], v[234:237], v[46:49], v[70:73]
	v_mfma_f32_16x16x32_bf16 v[82:85], v[238:241], v[54:57], v[14:17]
	v_mfma_f32_16x16x32_bf16 v[14:17], v[226:229], v[58:61], v[50:53]
	v_mfma_f32_16x16x32_bf16 v[50:53], v[230:233], v[62:65], v[14:17]
	v_mfma_f32_16x16x32_bf16 v[14:17], v[234:237], v[58:61], v[34:37]
	v_mfma_f32_16x16x32_bf16 v[6:9], v[226:229], v[66:69], v[6:9]
	v_mfma_f32_16x16x32_bf16 v[2:5], v[234:237], v[66:69], v[2:5]
	v_mfma_f32_16x16x32_bf16 v[34:37], v[238:241], v[62:65], v[14:17]
	v_mfma_f32_16x16x32_bf16 v[6:9], v[230:233], v[178:181], v[6:9]
	v_mfma_f32_16x16x32_bf16 v[2:5], v[238:241], v[178:181], v[2:5]
	s_setprio 0
	s_add_i32 s57, s57, 2
	s_add_u32 s55, s55, 0x100
	s_addc_u32 s56, s56, 0
	s_cmp_gt_u32 s57, 13
	s_mov_b64 s[4:5], s[36:37]
	s_barrier

.LBB0_1098:
	s_add_i32 s76, s76, 1
	s_mov_b64 s[62:63], s[54:55]
	s_mul_i32 s54, s76, s26
	s_add_i32 s64, s54, s2
	s_cmpk_gt_i32 s64, 0x57f
	s_cselect_b64 s[60:61], -1, 0
	s_lshl_b32 s54, s64, 3
	s_and_b32 s54, s54, 56
	s_bfe_u32 s55, s64, 0x30003
	s_or_b32 s77, s54, s55
	s_ashr_i32 s58, s64, 6
	s_lshl_b32 s54, s77, 19
	s_mov_b64 s[36:37], s[56:57]
	s_add_u32 s56, s52, s54
	s_addc_u32 s57, s53, 0
	s_ashr_i32 s59, s58, 31
	s_lshl_b64 s[54:55], s[58:59], 19
	s_add_u32 s54, s4, s54
	s_addc_u32 s55, s5, s55
	s_cmpk_lt_i32 s64, 0x580
	s_cselect_b32 s59, s57, s37
	s_cselect_b32 s78, s56, s36
	s_cselect_b32 s79, s55, s63
	s_cselect_b32 s80, s54, s62
	s_add_u32 s81, s62, 0x100
	s_addc_u32 s82, s63, 0
	s_mov_b32 s83, -2
	s_add_u32 s62, s36, 0x100
	s_addc_u32 s63, s37, 0
	s_add_i32 s84, 0, 0x10000
	v_add_u32_e32 v70, s84, v170
	ds_read_b128 v[58:61], v70
	ds_read_b128 v[62:65], v70 offset:1024
	ds_read_b128 v[66:69], v70 offset:2048
	ds_read_b128 v[70:73], v70 offset:3072
	s_cmp_eq_u32 s83, 12
	s_cselect_b32 s67, s59, s63
	s_cselect_b32 s66, s78, s62
	s_cselect_b32 s65, s79, s82
	s_cselect_b32 s64, s80, s81
	v_lshl_add_u64 v[192:193], s[36:37], 0, v[168:169]
	s_add_i32 m0, s69, 0xc000
	ds_read_b128 v[78:81], v175
	ds_read_b128 v[86:89], v175 offset:1024
	ds_read_b128 v[90:93], v175 offset:2048
	ds_read_b128 v[94:97], v175 offset:3072
	ds_read_b128 v[176:179], v175 offset:4096
	ds_read_b128 v[180:183], v175 offset:5120
	ds_read_b128 v[184:187], v175 offset:6144
	ds_read_b128 v[188:191], v175 offset:7168
	global_load_lds_dwordx4 v[192:193], off
	v_lshl_add_u64 v[192:193], s[36:37], 0, v[166:167]
	s_add_i32 m0, s69, 0xe000
	s_nop 0
	global_load_lds_dwordx4 v[192:193], off
	s_waitcnt lgkmcnt(8)
	s_barrier
	s_waitcnt lgkmcnt(0)
	s_setprio 1
	s_waitcnt lgkmcnt(0)
	v_mfma_f32_16x16x32_bf16 v[158:161], v[58:61], v[78:81], 0
	v_mfma_f32_16x16x32_bf16 v[150:153], v[66:69], v[78:81], 0
	v_mfma_f32_16x16x32_bf16 v[142:145], v[58:61], v[90:93], 0
	v_mfma_f32_16x16x32_bf16 v[134:137], v[66:69], v[90:93], 0
	v_mfma_f32_16x16x32_bf16 v[126:129], v[58:61], v[176:179], 0
	v_mfma_f32_16x16x32_bf16 v[118:121], v[66:69], v[176:179], 0
	v_mfma_f32_16x16x32_bf16 v[110:113], v[58:61], v[184:187], 0
	v_mfma_f32_16x16x32_bf16 v[102:105], v[66:69], v[184:187], 0
	v_mfma_f32_16x16x32_bf16 v[158:161], v[62:65], v[86:89], v[158:161]
	v_mfma_f32_16x16x32_bf16 v[150:153], v[70:73], v[86:89], v[150:153]
	v_mfma_f32_16x16x32_bf16 v[142:145], v[62:65], v[94:97], v[142:145]
	v_mfma_f32_16x16x32_bf16 v[134:137], v[70:73], v[94:97], v[134:137]
	v_mfma_f32_16x16x32_bf16 v[126:129], v[62:65], v[180:183], v[126:129]
	v_mfma_f32_16x16x32_bf16 v[118:121], v[70:73], v[180:183], v[118:121]
	v_mfma_f32_16x16x32_bf16 v[110:113], v[62:65], v[188:191], v[110:113]
	v_mfma_f32_16x16x32_bf16 v[102:105], v[70:73], v[188:191], v[102:105]
	s_setprio 0
	s_barrier
	s_add_i32 s85, 0, 0x14000
	v_add_u32_e32 v192, s85, v170
	s_add_i32 s36, s84, s68
	ds_read_b128 v[200:203], v192
	ds_read_b128 v[204:207], v192 offset:1024
	ds_read_b128 v[208:211], v192 offset:2048
	ds_read_b128 v[222:225], v192 offset:3072
	v_lshl_add_u64 v[192:193], s[64:65], 0, v[164:165]
	s_mov_b32 m0, s36
	v_lshl_add_u64 v[214:215], s[64:65], 0, v[162:163]
	global_load_lds_dwordx4 v[192:193], off
	s_add_i32 m0, s36, 0x2000
	s_nop 0
	global_load_lds_dwordx4 v[214:215], off
	s_barrier
	s_waitcnt lgkmcnt(0)
	s_setprio 1
	s_waitcnt lgkmcnt(0)
	v_mfma_f32_16x16x32_bf16 v[154:157], v[200:203], v[78:81], 0
	v_mfma_f32_16x16x32_bf16 v[78:81], v[208:211], v[78:81], 0
	v_mfma_f32_16x16x32_bf16 v[154:157], v[204:207], v[86:89], v[154:157]
	v_mfma_f32_16x16x32_bf16 v[78:81], v[222:225], v[86:89], v[78:81]
	v_mfma_f32_16x16x32_bf16 v[86:89], v[200:203], v[90:93], 0
	v_mfma_f32_16x16x32_bf16 v[90:93], v[208:211], v[90:93], 0
	v_mfma_f32_16x16x32_bf16 v[114:117], v[208:211], v[176:179], 0
	v_mfma_f32_16x16x32_bf16 v[106:109], v[200:203], v[184:187], 0
	v_mfma_f32_16x16x32_bf16 v[98:101], v[208:211], v[184:187], 0
	v_mfma_f32_16x16x32_bf16 v[86:89], v[204:207], v[94:97], v[86:89]
	v_mfma_f32_16x16x32_bf16 v[90:93], v[222:225], v[94:97], v[90:93]
	v_mfma_f32_16x16x32_bf16 v[94:97], v[200:203], v[176:179], 0
	v_mfma_f32_16x16x32_bf16 v[114:117], v[222:225], v[180:183], v[114:117]
	v_mfma_f32_16x16x32_bf16 v[106:109], v[204:207], v[188:191], v[106:109]
	v_mfma_f32_16x16x32_bf16 v[98:101], v[222:225], v[188:191], v[98:101]
	v_mfma_f32_16x16x32_bf16 v[94:97], v[204:207], v[180:183], v[94:97]
	s_setprio 0
	s_mov_b32 m0, s69
	v_lshl_add_u64 v[234:235], s[66:67], 0, v[164:165]
	s_barrier
	ds_read_b128 v[122:125], v175 offset:16384
	ds_read_b128 v[130:133], v175 offset:17408
	ds_read_b128 v[138:141], v175 offset:18432
	ds_read_b128 v[146:149], v175 offset:19456
	ds_read_b128 v[176:179], v175 offset:20480
	ds_read_b128 v[180:183], v175 offset:21504
	ds_read_b128 v[184:187], v175 offset:22528
	ds_read_b128 v[188:191], v175 offset:23552
	global_load_lds_dwordx4 v[234:235], off
	v_lshl_add_u64 v[236:237], s[66:67], 0, v[162:163]
	s_mov_b32 m0, s70
	s_nop 0
	global_load_lds_dwordx4 v[236:237], off
	s_barrier
	s_waitcnt lgkmcnt(0)
	s_setprio 1
	s_waitcnt lgkmcnt(0)
	v_mfma_f32_16x16x32_bf16 v[82:85], v[58:61], v[122:125], 0
	v_mfma_f32_16x16x32_bf16 v[54:57], v[66:69], v[122:125], 0
	v_mfma_f32_16x16x32_bf16 v[46:49], v[58:61], v[138:141], 0
	v_mfma_f32_16x16x32_bf16 v[38:41], v[66:69], v[138:141], 0
	v_mfma_f32_16x16x32_bf16 v[30:33], v[58:61], v[176:179], 0
	v_mfma_f32_16x16x32_bf16 v[22:25], v[66:69], v[176:179], 0
	v_mfma_f32_16x16x32_bf16 v[14:17], v[58:61], v[184:187], 0
	v_mfma_f32_16x16x32_bf16 v[6:9], v[66:69], v[184:187], 0
	v_mfma_f32_16x16x32_bf16 v[82:85], v[62:65], v[130:133], v[82:85]
	v_mfma_f32_16x16x32_bf16 v[54:57], v[70:73], v[130:133], v[54:57]
	v_mfma_f32_16x16x32_bf16 v[46:49], v[62:65], v[146:149], v[46:49]
	v_mfma_f32_16x16x32_bf16 v[38:41], v[70:73], v[146:149], v[38:41]
	v_mfma_f32_16x16x32_bf16 v[30:33], v[62:65], v[180:183], v[30:33]
	v_mfma_f32_16x16x32_bf16 v[22:25], v[70:73], v[180:183], v[22:25]
	v_mfma_f32_16x16x32_bf16 v[14:17], v[62:65], v[188:191], v[14:17]
	v_mfma_f32_16x16x32_bf16 v[6:9], v[70:73], v[188:191], v[6:9]
	s_setprio 0
	s_barrier
	s_add_u32 s36, s64, 0x40000
	s_addc_u32 s37, s65, 0
	s_add_i32 s84, s85, s68
	v_lshl_add_u64 v[58:59], s[36:37], 0, v[164:165]
	s_mov_b32 m0, s84
	s_nop 0
	global_load_lds_dwordx4 v[58:59], off
	v_lshl_add_u64 v[58:59], s[36:37], 0, v[162:163]
	s_add_i32 m0, s84, 0x2000
	s_nop 0
	global_load_lds_dwordx4 v[58:59], off
	s_waitcnt vmcnt(6)
	s_barrier
	s_setprio 1
	v_mfma_f32_16x16x32_bf16 v[50:53], v[208:211], v[122:125], 0
	v_mfma_f32_16x16x32_bf16 v[42:45], v[200:203], v[138:141], 0
	v_mfma_f32_16x16x32_bf16 v[34:37], v[208:211], v[138:141], 0
	v_mfma_f32_16x16x32_bf16 v[26:29], v[200:203], v[176:179], 0
	v_mfma_f32_16x16x32_bf16 v[18:21], v[208:211], v[176:179], 0
	v_mfma_f32_16x16x32_bf16 v[10:13], v[200:203], v[184:187], 0
	v_mfma_f32_16x16x32_bf16 v[2:5], v[208:211], v[184:187], 0
	v_mfma_f32_16x16x32_bf16 v[58:61], v[200:203], v[122:125], 0
	v_mfma_f32_16x16x32_bf16 v[50:53], v[222:225], v[130:133], v[50:53]
	v_mfma_f32_16x16x32_bf16 v[42:45], v[204:207], v[146:149], v[42:45]
	v_mfma_f32_16x16x32_bf16 v[34:37], v[222:225], v[146:149], v[34:37]
	v_mfma_f32_16x16x32_bf16 v[26:29], v[204:207], v[180:183], v[26:29]
	v_mfma_f32_16x16x32_bf16 v[18:21], v[222:225], v[180:183], v[18:21]
	v_mfma_f32_16x16x32_bf16 v[10:13], v[204:207], v[188:191], v[10:13]
	v_mfma_f32_16x16x32_bf16 v[2:5], v[222:225], v[188:191], v[2:5]
	v_mfma_f32_16x16x32_bf16 v[58:61], v[204:207], v[130:133], v[58:61]
	s_setprio 0
	s_add_i32 s84, 0, 0x18000
	v_add_u32_e32 v74, s84, v170
	s_barrier
	ds_read_b128 v[62:65], v74
	ds_read_b128 v[66:69], v74 offset:1024
	ds_read_b128 v[70:73], v74 offset:2048
	ds_read_b128 v[74:77], v74 offset:3072
	s_add_u32 s36, s66, 0x40000
	s_addc_u32 s37, s67, 0
	s_mov_b32 m0, s71
	v_lshl_add_u64 v[138:139], s[36:37], 0, v[164:165]
	ds_read_b128 v[122:125], v175 offset:32768
	ds_read_b128 v[130:133], v175 offset:33792
	ds_read_b128 v[176:179], v175 offset:34816
	ds_read_b128 v[180:183], v175 offset:35840
	ds_read_b128 v[184:187], v175 offset:36864
	ds_read_b128 v[188:191], v175 offset:37888
	ds_read_b128 v[200:203], v175 offset:38912
	ds_read_b128 v[204:207], v175 offset:39936
	global_load_lds_dwordx4 v[138:139], off
	v_lshl_add_u64 v[138:139], s[36:37], 0, v[162:163]
	s_mov_b32 m0, s72
	s_nop 0
	global_load_lds_dwordx4 v[138:139], off
	s_waitcnt lgkmcnt(8)
	s_barrier
	s_waitcnt lgkmcnt(0)
	s_setprio 1
	s_waitcnt lgkmcnt(0)
	v_mfma_f32_16x16x32_bf16 v[138:141], v[62:65], v[122:125], v[158:161]
	v_mfma_f32_16x16x32_bf16 v[158:161], v[66:69], v[130:133], v[138:141]
	v_mfma_f32_16x16x32_bf16 v[138:141], v[70:73], v[122:125], v[150:153]
	v_mfma_f32_16x16x32_bf16 v[150:153], v[74:77], v[130:133], v[138:141]
	v_mfma_f32_16x16x32_bf16 v[138:141], v[62:65], v[176:179], v[142:145]
	v_mfma_f32_16x16x32_bf16 v[134:137], v[70:73], v[176:179], v[134:137]
	v_mfma_f32_16x16x32_bf16 v[126:129], v[62:65], v[184:187], v[126:129]
	v_mfma_f32_16x16x32_bf16 v[118:121], v[70:73], v[184:187], v[118:121]
	v_mfma_f32_16x16x32_bf16 v[110:113], v[62:65], v[200:203], v[110:113]
	v_mfma_f32_16x16x32_bf16 v[102:105], v[70:73], v[200:203], v[102:105]
	v_mfma_f32_16x16x32_bf16 v[142:145], v[66:69], v[180:183], v[138:141]
	v_mfma_f32_16x16x32_bf16 v[134:137], v[74:77], v[180:183], v[134:137]
	v_mfma_f32_16x16x32_bf16 v[126:129], v[66:69], v[188:191], v[126:129]
	v_mfma_f32_16x16x32_bf16 v[118:121], v[74:77], v[188:191], v[118:121]
	v_mfma_f32_16x16x32_bf16 v[110:113], v[66:69], v[204:207], v[110:113]
	v_mfma_f32_16x16x32_bf16 v[102:105], v[74:77], v[204:207], v[102:105]
	s_setprio 0
	s_barrier
	s_add_i32 s66, 0, 0x1c000
	v_add_u32_e32 v138, s66, v170
	s_add_i32 s36, s84, s68
	ds_read_b128 v[208:211], v138
	ds_read_b128 v[222:225], v138 offset:1024
	ds_read_b128 v[226:229], v138 offset:2048
	ds_read_b128 v[230:233], v138 offset:3072
	v_lshl_add_u64 v[138:139], v[192:193], 0, s[22:23]
	s_mov_b32 m0, s36
	s_nop 0
	global_load_lds_dwordx4 v[138:139], off
	v_lshl_add_u64 v[138:139], v[214:215], 0, s[22:23]
	s_add_i32 m0, s36, 0x2000
	s_nop 0
	global_load_lds_dwordx4 v[138:139], off
	s_barrier
	s_waitcnt lgkmcnt(0)
	s_setprio 1
	s_waitcnt lgkmcnt(0)
	v_mfma_f32_16x16x32_bf16 v[78:81], v[226:229], v[122:125], v[78:81]
	v_mfma_f32_16x16x32_bf16 v[138:141], v[208:211], v[122:125], v[154:157]
	v_mfma_f32_16x16x32_bf16 v[146:149], v[230:233], v[130:133], v[78:81]
	v_mfma_f32_16x16x32_bf16 v[78:81], v[208:211], v[176:179], v[86:89]
	v_mfma_f32_16x16x32_bf16 v[154:157], v[222:225], v[130:133], v[138:141]
	v_mfma_f32_16x16x32_bf16 v[138:141], v[222:225], v[180:183], v[78:81]
	v_mfma_f32_16x16x32_bf16 v[78:81], v[226:229], v[176:179], v[90:93]
	v_mfma_f32_16x16x32_bf16 v[130:133], v[230:233], v[180:183], v[78:81]
	v_mfma_f32_16x16x32_bf16 v[78:81], v[208:211], v[184:187], v[94:97]
	v_mfma_f32_16x16x32_bf16 v[122:125], v[222:225], v[188:191], v[78:81]
	v_mfma_f32_16x16x32_bf16 v[78:81], v[226:229], v[184:187], v[114:117]
	v_mfma_f32_16x16x32_bf16 v[114:117], v[230:233], v[188:191], v[78:81]
	v_mfma_f32_16x16x32_bf16 v[78:81], v[208:211], v[200:203], v[106:109]
	v_mfma_f32_16x16x32_bf16 v[106:109], v[222:225], v[204:207], v[78:81]
	v_mfma_f32_16x16x32_bf16 v[78:81], v[226:229], v[200:203], v[98:101]
	v_mfma_f32_16x16x32_bf16 v[98:101], v[230:233], v[204:207], v[78:81]
	s_setprio 0
	s_mov_b32 m0, s73
	v_lshl_add_u64 v[192:193], v[234:235], 0, s[22:23]
	s_barrier
	s_nop 2
	ds_read_b128 v[78:81], v175 offset:49152
	ds_read_b128 v[86:89], v175 offset:50176
	ds_read_b128 v[90:93], v175 offset:51200
	ds_read_b128 v[94:97], v175 offset:52224
	ds_read_b128 v[176:179], v175 offset:53248
	ds_read_b128 v[180:183], v175 offset:54272
	ds_read_b128 v[184:187], v175 offset:55296
	ds_read_b128 v[188:191], v175 offset:56320
	global_load_lds_dwordx4 v[192:193], off
	v_lshl_add_u64 v[192:193], v[236:237], 0, s[22:23]
	s_mov_b32 m0, s75
	s_nop 0
	global_load_lds_dwordx4 v[192:193], off
	s_barrier
	s_waitcnt lgkmcnt(0)
	s_setprio 1
	s_waitcnt lgkmcnt(0)
	v_mfma_f32_16x16x32_bf16 v[82:85], v[62:65], v[78:81], v[82:85]
	v_mfma_f32_16x16x32_bf16 v[54:57], v[70:73], v[78:81], v[54:57]
	v_mfma_f32_16x16x32_bf16 v[46:49], v[62:65], v[90:93], v[46:49]
	v_mfma_f32_16x16x32_bf16 v[38:41], v[70:73], v[90:93], v[38:41]
	v_mfma_f32_16x16x32_bf16 v[30:33], v[62:65], v[176:179], v[30:33]
	v_mfma_f32_16x16x32_bf16 v[22:25], v[70:73], v[176:179], v[22:25]
	v_mfma_f32_16x16x32_bf16 v[14:17], v[62:65], v[184:187], v[14:17]
	v_mfma_f32_16x16x32_bf16 v[6:9], v[70:73], v[184:187], v[6:9]
	v_mfma_f32_16x16x32_bf16 v[82:85], v[66:69], v[86:89], v[82:85]
	v_mfma_f32_16x16x32_bf16 v[54:57], v[74:77], v[86:89], v[54:57]
	v_mfma_f32_16x16x32_bf16 v[46:49], v[66:69], v[94:97], v[46:49]
	v_mfma_f32_16x16x32_bf16 v[38:41], v[74:77], v[94:97], v[38:41]
	v_mfma_f32_16x16x32_bf16 v[30:33], v[66:69], v[180:183], v[30:33]
	v_mfma_f32_16x16x32_bf16 v[22:25], v[74:77], v[180:183], v[22:25]
	v_mfma_f32_16x16x32_bf16 v[14:17], v[66:69], v[188:191], v[14:17]
	v_mfma_f32_16x16x32_bf16 v[6:9], v[74:77], v[188:191], v[6:9]
	s_setprio 0
	s_barrier
	s_add_u32 s36, s64, 0x40080
	s_addc_u32 s37, s65, 0
	s_add_i32 s64, s66, s68
	v_lshl_add_u64 v[62:63], s[36:37], 0, v[164:165]
	s_mov_b32 m0, s64
	s_nop 0
	global_load_lds_dwordx4 v[62:63], off
	v_lshl_add_u64 v[62:63], s[36:37], 0, v[162:163]
	s_add_i32 m0, s64, 0x2000
	s_nop 0
	global_load_lds_dwordx4 v[62:63], off
	s_waitcnt vmcnt(6)
	s_barrier
	s_setprio 1
	v_mfma_f32_16x16x32_bf16 v[58:61], v[208:211], v[78:81], v[58:61]
	v_mfma_f32_16x16x32_bf16 v[50:53], v[226:229], v[78:81], v[50:53]
	v_mfma_f32_16x16x32_bf16 v[42:45], v[208:211], v[90:93], v[42:45]
	v_mfma_f32_16x16x32_bf16 v[34:37], v[226:229], v[90:93], v[34:37]
	v_mfma_f32_16x16x32_bf16 v[26:29], v[208:211], v[176:179], v[26:29]
	v_mfma_f32_16x16x32_bf16 v[18:21], v[226:229], v[176:179], v[18:21]
	v_mfma_f32_16x16x32_bf16 v[10:13], v[208:211], v[184:187], v[10:13]
	v_mfma_f32_16x16x32_bf16 v[2:5], v[226:229], v[184:187], v[2:5]
	v_mfma_f32_16x16x32_bf16 v[74:77], v[222:225], v[86:89], v[58:61]
	v_mfma_f32_16x16x32_bf16 v[50:53], v[230:233], v[86:89], v[50:53]
	v_mfma_f32_16x16x32_bf16 v[42:45], v[222:225], v[94:97], v[42:45]
	v_mfma_f32_16x16x32_bf16 v[34:37], v[230:233], v[94:97], v[34:37]
	v_mfma_f32_16x16x32_bf16 v[26:29], v[222:225], v[180:183], v[26:29]
	v_mfma_f32_16x16x32_bf16 v[18:21], v[230:233], v[180:183], v[18:21]
	v_mfma_f32_16x16x32_bf16 v[10:13], v[222:225], v[188:191], v[10:13]
	v_mfma_f32_16x16x32_bf16 v[2:5], v[230:233], v[188:191], v[2:5]
	s_setprio 0
	s_add_i32 s83, s83, 2
	s_add_u32 s81, s81, 0x100
	s_addc_u32 s82, s82, 0
	s_cmp_gt_u32 s83, 13
	s_mov_b64 s[36:37], s[62:63]
	s_barrier

.LBB0_1178:
	s_add_u32 s27, s36, 0x100
	s_addc_u32 s91, s37, 0
	s_add_u32 s36, s42, 0x80
	s_addc_u32 s37, s43, 0
	s_mov_b32 s42, 0
	s_waitcnt lgkmcnt(0)
	s_add_i32 s92, s42, 2
	s_add_u32 s72, s36, 0x80
	s_addc_u32 s43, s37, 0
	s_add_i32 s93, 0, 0x10000
	v_add_u32_e32 v1, s93, v223
	ds_read_b128 v[50:53], v1
	ds_read_b128 v[54:57], v1 offset:1024
	ds_read_b128 v[58:61], v1 offset:2048
	ds_read_b128 v[62:65], v1 offset:3072
	s_cmp_eq_u32 s88, s42
	s_cselect_b32 s42, s66, s72
	s_cselect_b32 s43, s67, s43
	s_cselect_b32 s73, s71, s91
	s_cselect_b32 s72, s70, s27
	v_lshl_add_u64 v[178:179], s[36:37], 0, v[206:207]
	s_add_i32 m0, s79, 0xc000
	ds_read_b128 v[66:69], v230
	ds_read_b128 v[70:73], v230 offset:1024
	ds_read_b128 v[74:77], v230 offset:2048
	ds_read_b128 v[78:81], v230 offset:3072
	ds_read_b128 v[146:149], v230 offset:4096
	ds_read_b128 v[154:157], v230 offset:5120
	ds_read_b128 v[170:173], v230 offset:6144
	ds_read_b128 v[174:177], v230 offset:7168
	global_load_lds_dwordx4 v[178:179], off
	v_lshl_add_u64 v[178:179], s[36:37], 0, v[204:205]
	s_add_i32 m0, s79, 0xe000
	s_nop 0
	global_load_lds_dwordx4 v[178:179], off
	s_waitcnt lgkmcnt(8)
	s_barrier
	s_waitcnt lgkmcnt(0)
	s_setprio 1
	s_waitcnt lgkmcnt(0)
	v_mfma_f32_16x16x32_bf16 v[166:169], v[50:53], v[66:69], 0
	v_mfma_f32_16x16x32_bf16 v[162:165], v[58:61], v[66:69], 0
	v_mfma_f32_16x16x32_bf16 v[142:145], v[50:53], v[74:77], 0
	v_mfma_f32_16x16x32_bf16 v[138:141], v[58:61], v[74:77], 0
	v_mfma_f32_16x16x32_bf16 v[126:129], v[50:53], v[146:149], 0
	v_mfma_f32_16x16x32_bf16 v[122:125], v[58:61], v[146:149], 0
	v_mfma_f32_16x16x32_bf16 v[110:113], v[50:53], v[170:173], 0
	v_mfma_f32_16x16x32_bf16 v[106:109], v[58:61], v[170:173], 0
	v_mfma_f32_16x16x32_bf16 v[166:169], v[54:57], v[70:73], v[166:169]
	v_mfma_f32_16x16x32_bf16 v[162:165], v[62:65], v[70:73], v[162:165]
	v_mfma_f32_16x16x32_bf16 v[142:145], v[54:57], v[78:81], v[142:145]
	v_mfma_f32_16x16x32_bf16 v[138:141], v[62:65], v[78:81], v[138:141]
	v_mfma_f32_16x16x32_bf16 v[126:129], v[54:57], v[154:157], v[126:129]
	v_mfma_f32_16x16x32_bf16 v[122:125], v[62:65], v[154:157], v[122:125]
	v_mfma_f32_16x16x32_bf16 v[110:113], v[54:57], v[174:177], v[110:113]
	v_mfma_f32_16x16x32_bf16 v[106:109], v[62:65], v[174:177], v[106:109]
	s_setprio 0
	s_barrier
	s_add_i32 s94, 0, 0x14000
	s_add_i32 s93, s93, s78
	v_add_u32_e32 v1, s94, v223
	v_lshl_add_u64 v[214:215], s[72:73], 0, v[202:203]
	s_mov_b32 m0, s93
	ds_read_b128 v[178:181], v1
	ds_read_b128 v[182:185], v1 offset:1024
	ds_read_b128 v[186:189], v1 offset:2048
	ds_read_b128 v[190:193], v1 offset:3072
	global_load_lds_dwordx4 v[214:215], off
	v_lshl_add_u64 v[236:237], s[72:73], 0, v[200:201]
	s_add_i32 m0, s93, 0x2000
	s_nop 0
	global_load_lds_dwordx4 v[236:237], off
	s_barrier
	s_waitcnt lgkmcnt(0)
	s_setprio 1
	s_waitcnt lgkmcnt(0)
	v_mfma_f32_16x16x32_bf16 v[158:161], v[178:181], v[66:69], 0
	v_mfma_f32_16x16x32_bf16 v[66:69], v[186:189], v[66:69], 0
	v_mfma_f32_16x16x32_bf16 v[158:161], v[182:185], v[70:73], v[158:161]
	v_mfma_f32_16x16x32_bf16 v[66:69], v[190:193], v[70:73], v[66:69]
	v_mfma_f32_16x16x32_bf16 v[70:73], v[178:181], v[74:77], 0
	v_mfma_f32_16x16x32_bf16 v[74:77], v[186:189], v[74:77], 0
	v_mfma_f32_16x16x32_bf16 v[114:117], v[186:189], v[146:149], 0
	v_mfma_f32_16x16x32_bf16 v[102:105], v[178:181], v[170:173], 0
	v_mfma_f32_16x16x32_bf16 v[98:101], v[186:189], v[170:173], 0
	v_mfma_f32_16x16x32_bf16 v[70:73], v[182:185], v[78:81], v[70:73]
	v_mfma_f32_16x16x32_bf16 v[74:77], v[190:193], v[78:81], v[74:77]
	v_mfma_f32_16x16x32_bf16 v[78:81], v[178:181], v[146:149], 0
	v_mfma_f32_16x16x32_bf16 v[114:117], v[190:193], v[154:157], v[114:117]
	v_mfma_f32_16x16x32_bf16 v[102:105], v[182:185], v[174:177], v[102:105]
	v_mfma_f32_16x16x32_bf16 v[98:101], v[190:193], v[174:177], v[98:101]
	v_mfma_f32_16x16x32_bf16 v[78:81], v[182:185], v[154:157], v[78:81]
	s_setprio 0
	s_mov_b32 m0, s79
	v_lshl_add_u64 v[238:239], s[42:43], 0, v[202:203]
	s_barrier
	ds_read_b128 v[118:121], v230 offset:16384
	ds_read_b128 v[130:133], v230 offset:17408
	ds_read_b128 v[134:137], v230 offset:18432
	ds_read_b128 v[146:149], v230 offset:19456
	ds_read_b128 v[150:153], v230 offset:20480
	ds_read_b128 v[154:157], v230 offset:21504
	ds_read_b128 v[170:173], v230 offset:22528
	ds_read_b128 v[174:177], v230 offset:23552
	global_load_lds_dwordx4 v[238:239], off
	v_lshl_add_u64 v[240:241], s[42:43], 0, v[200:201]
	s_mov_b32 m0, s80
	s_nop 0
	global_load_lds_dwordx4 v[240:241], off
	s_barrier
	s_waitcnt lgkmcnt(0)
	s_setprio 1
	s_waitcnt lgkmcnt(0)
	v_mfma_f32_16x16x32_bf16 v[94:97], v[50:53], v[118:121], 0
	v_mfma_f32_16x16x32_bf16 v[90:93], v[58:61], v[118:121], 0
	v_mfma_f32_16x16x32_bf16 v[46:49], v[50:53], v[134:137], 0
	v_mfma_f32_16x16x32_bf16 v[42:45], v[58:61], v[134:137], 0
	v_mfma_f32_16x16x32_bf16 v[30:33], v[50:53], v[150:153], 0
	v_mfma_f32_16x16x32_bf16 v[26:29], v[58:61], v[150:153], 0
	v_mfma_f32_16x16x32_bf16 v[14:17], v[50:53], v[170:173], 0
	v_mfma_f32_16x16x32_bf16 v[10:13], v[58:61], v[170:173], 0
	v_mfma_f32_16x16x32_bf16 v[94:97], v[54:57], v[130:133], v[94:97]
	v_mfma_f32_16x16x32_bf16 v[90:93], v[62:65], v[130:133], v[90:93]
	v_mfma_f32_16x16x32_bf16 v[46:49], v[54:57], v[146:149], v[46:49]
	v_mfma_f32_16x16x32_bf16 v[42:45], v[62:65], v[146:149], v[42:45]
	v_mfma_f32_16x16x32_bf16 v[30:33], v[54:57], v[154:157], v[30:33]
	v_mfma_f32_16x16x32_bf16 v[26:29], v[62:65], v[154:157], v[26:29]
	v_mfma_f32_16x16x32_bf16 v[14:17], v[54:57], v[174:177], v[14:17]
	v_mfma_f32_16x16x32_bf16 v[10:13], v[62:65], v[174:177], v[10:13]
	s_setprio 0
	s_barrier
	s_add_u32 s72, s72, s4
	s_addc_u32 s73, s73, 0
	s_add_i32 s93, s94, s78
	v_lshl_add_u64 v[242:243], s[72:73], 0, v[202:203]
	s_mov_b32 m0, s93
	v_lshl_add_u64 v[244:245], s[72:73], 0, v[200:201]
	global_load_lds_dwordx4 v[242:243], off
	s_add_i32 m0, s93, 0x2000
	s_nop 0
	global_load_lds_dwordx4 v[244:245], off
	s_waitcnt vmcnt(6)
	s_barrier
	s_setprio 1
	v_mfma_f32_16x16x32_bf16 v[38:41], v[178:181], v[134:137], 0
	v_mfma_f32_16x16x32_bf16 v[34:37], v[186:189], v[134:137], 0
	v_mfma_f32_16x16x32_bf16 v[22:25], v[178:181], v[150:153], 0
	v_mfma_f32_16x16x32_bf16 v[18:21], v[186:189], v[150:153], 0
	v_mfma_f32_16x16x32_bf16 v[6:9], v[178:181], v[170:173], 0
	v_mfma_f32_16x16x32_bf16 v[2:5], v[186:189], v[170:173], 0
	v_mfma_f32_16x16x32_bf16 v[50:53], v[178:181], v[118:121], 0
	v_mfma_f32_16x16x32_bf16 v[54:57], v[186:189], v[118:121], 0
	v_mfma_f32_16x16x32_bf16 v[38:41], v[182:185], v[146:149], v[38:41]
	v_mfma_f32_16x16x32_bf16 v[34:37], v[190:193], v[146:149], v[34:37]
	v_mfma_f32_16x16x32_bf16 v[22:25], v[182:185], v[154:157], v[22:25]
	v_mfma_f32_16x16x32_bf16 v[18:21], v[190:193], v[154:157], v[18:21]
	v_mfma_f32_16x16x32_bf16 v[6:9], v[182:185], v[174:177], v[6:9]
	v_mfma_f32_16x16x32_bf16 v[2:5], v[190:193], v[174:177], v[2:5]
	v_mfma_f32_16x16x32_bf16 v[50:53], v[182:185], v[130:133], v[50:53]
	v_mfma_f32_16x16x32_bf16 v[54:57], v[190:193], v[130:133], v[54:57]
	s_setprio 0
	s_add_i32 s72, 0, 0x18000
	v_add_u32_e32 v1, s72, v223
	s_barrier
	ds_read_b128 v[58:61], v1
	ds_read_b128 v[62:65], v1 offset:1024
	ds_read_b128 v[82:85], v1 offset:2048
	ds_read_b128 v[86:89], v1 offset:3072
	s_add_u32 s42, s42, s4
	s_addc_u32 s43, s43, 0
	s_mov_b32 m0, s81
	v_lshl_add_u64 v[134:135], s[42:43], 0, v[202:203]
	ds_read_b128 v[118:121], v230 offset:32768
	ds_read_b128 v[130:133], v230 offset:33792
	ds_read_b128 v[146:149], v230 offset:34816
	ds_read_b128 v[154:157], v230 offset:35840
	ds_read_b128 v[170:173], v230 offset:36864
	ds_read_b128 v[174:177], v230 offset:37888
	ds_read_b128 v[178:181], v230 offset:38912
	ds_read_b128 v[182:185], v230 offset:39936
	global_load_lds_dwordx4 v[134:135], off
	v_lshl_add_u64 v[134:135], s[42:43], 0, v[200:201]
	s_mov_b32 m0, s82
	s_nop 0
	global_load_lds_dwordx4 v[134:135], off
	s_waitcnt lgkmcnt(8)
	s_barrier
	s_waitcnt lgkmcnt(0)
	s_setprio 1
	s_waitcnt lgkmcnt(0)
	v_mfma_f32_16x16x32_bf16 v[134:137], v[58:61], v[118:121], v[166:169]
	v_mfma_f32_16x16x32_bf16 v[166:169], v[62:65], v[130:133], v[134:137]
	v_mfma_f32_16x16x32_bf16 v[134:137], v[82:85], v[118:121], v[162:165]
	v_mfma_f32_16x16x32_bf16 v[162:165], v[86:89], v[130:133], v[134:137]
	v_mfma_f32_16x16x32_bf16 v[134:137], v[58:61], v[146:149], v[142:145]
	v_mfma_f32_16x16x32_bf16 v[142:145], v[62:65], v[154:157], v[134:137]
	v_mfma_f32_16x16x32_bf16 v[134:137], v[82:85], v[146:149], v[138:141]
	v_mfma_f32_16x16x32_bf16 v[126:129], v[58:61], v[170:173], v[126:129]
	v_mfma_f32_16x16x32_bf16 v[122:125], v[82:85], v[170:173], v[122:125]
	v_mfma_f32_16x16x32_bf16 v[110:113], v[58:61], v[178:181], v[110:113]
	v_mfma_f32_16x16x32_bf16 v[106:109], v[82:85], v[178:181], v[106:109]
	v_mfma_f32_16x16x32_bf16 v[138:141], v[86:89], v[154:157], v[134:137]
	v_mfma_f32_16x16x32_bf16 v[126:129], v[62:65], v[174:177], v[126:129]
	v_mfma_f32_16x16x32_bf16 v[122:125], v[86:89], v[174:177], v[122:125]
	v_mfma_f32_16x16x32_bf16 v[110:113], v[62:65], v[182:185], v[110:113]
	v_mfma_f32_16x16x32_bf16 v[106:109], v[86:89], v[182:185], v[106:109]
	s_setprio 0
	s_barrier
	s_add_i32 s42, 0, 0x1c000
	s_add_i32 s43, s72, s78
	v_add_u32_e32 v1, s42, v223
	v_lshl_add_u64 v[134:135], v[214:215], 0, s[22:23]
	s_mov_b32 m0, s43
	ds_read_b128 v[186:189], v1
	ds_read_b128 v[190:193], v1 offset:1024
	ds_read_b128 v[208:211], v1 offset:2048
	ds_read_b128 v[232:235], v1 offset:3072
	global_load_lds_dwordx4 v[134:135], off
	v_lshl_add_u64 v[134:135], v[236:237], 0, s[22:23]
	s_add_i32 m0, s43, 0x2000
	s_nop 0
	global_load_lds_dwordx4 v[134:135], off
	s_barrier
	s_waitcnt lgkmcnt(0)
	s_setprio 1
	s_waitcnt lgkmcnt(0)
	v_mfma_f32_16x16x32_bf16 v[66:69], v[208:211], v[118:121], v[66:69]
	v_mfma_f32_16x16x32_bf16 v[134:137], v[186:189], v[118:121], v[158:161]
	v_mfma_f32_16x16x32_bf16 v[150:153], v[232:235], v[130:133], v[66:69]
	v_mfma_f32_16x16x32_bf16 v[66:69], v[186:189], v[146:149], v[70:73]
	v_mfma_f32_16x16x32_bf16 v[158:161], v[190:193], v[130:133], v[134:137]
	v_mfma_f32_16x16x32_bf16 v[134:137], v[190:193], v[154:157], v[66:69]
	v_mfma_f32_16x16x32_bf16 v[66:69], v[208:211], v[146:149], v[74:77]
	v_mfma_f32_16x16x32_bf16 v[130:133], v[232:235], v[154:157], v[66:69]
	v_mfma_f32_16x16x32_bf16 v[66:69], v[186:189], v[170:173], v[78:81]
	v_mfma_f32_16x16x32_bf16 v[118:121], v[190:193], v[174:177], v[66:69]
	v_mfma_f32_16x16x32_bf16 v[66:69], v[208:211], v[170:173], v[114:117]
	v_mfma_f32_16x16x32_bf16 v[114:117], v[232:235], v[174:177], v[66:69]
	v_mfma_f32_16x16x32_bf16 v[66:69], v[186:189], v[178:181], v[102:105]
	v_mfma_f32_16x16x32_bf16 v[102:105], v[190:193], v[182:185], v[66:69]
	v_mfma_f32_16x16x32_bf16 v[66:69], v[208:211], v[178:181], v[98:101]
	v_mfma_f32_16x16x32_bf16 v[98:101], v[232:235], v[182:185], v[66:69]
	s_setprio 0
	s_mov_b32 m0, s86
	v_lshl_add_u64 v[178:179], v[238:239], 0, s[22:23]
	s_barrier
	s_nop 2
	ds_read_b128 v[66:69], v230 offset:49152
	ds_read_b128 v[70:73], v230 offset:50176
	ds_read_b128 v[74:77], v230 offset:51200
	ds_read_b128 v[78:81], v230 offset:52224
	ds_read_b128 v[146:149], v230 offset:53248
	ds_read_b128 v[154:157], v230 offset:54272
	ds_read_b128 v[170:173], v230 offset:55296
	ds_read_b128 v[174:177], v230 offset:56320
	global_load_lds_dwordx4 v[178:179], off
	v_lshl_add_u64 v[178:179], v[240:241], 0, s[22:23]
	s_mov_b32 m0, s87
	s_nop 0
	global_load_lds_dwordx4 v[178:179], off
	s_barrier
	s_waitcnt lgkmcnt(0)
	s_setprio 1
	s_waitcnt lgkmcnt(0)
	v_mfma_f32_16x16x32_bf16 v[94:97], v[58:61], v[66:69], v[94:97]
	v_mfma_f32_16x16x32_bf16 v[90:93], v[82:85], v[66:69], v[90:93]
	v_mfma_f32_16x16x32_bf16 v[46:49], v[58:61], v[74:77], v[46:49]
	v_mfma_f32_16x16x32_bf16 v[42:45], v[82:85], v[74:77], v[42:45]
	v_mfma_f32_16x16x32_bf16 v[30:33], v[58:61], v[146:149], v[30:33]
	v_mfma_f32_16x16x32_bf16 v[26:29], v[82:85], v[146:149], v[26:29]
	v_mfma_f32_16x16x32_bf16 v[14:17], v[58:61], v[170:173], v[14:17]
	v_mfma_f32_16x16x32_bf16 v[10:13], v[82:85], v[170:173], v[10:13]
	v_mfma_f32_16x16x32_bf16 v[94:97], v[62:65], v[70:73], v[94:97]
	v_mfma_f32_16x16x32_bf16 v[90:93], v[86:89], v[70:73], v[90:93]
	v_mfma_f32_16x16x32_bf16 v[46:49], v[62:65], v[78:81], v[46:49]
	v_mfma_f32_16x16x32_bf16 v[42:45], v[86:89], v[78:81], v[42:45]
	v_mfma_f32_16x16x32_bf16 v[30:33], v[62:65], v[154:157], v[30:33]
	v_mfma_f32_16x16x32_bf16 v[26:29], v[86:89], v[154:157], v[26:29]
	v_mfma_f32_16x16x32_bf16 v[14:17], v[62:65], v[174:177], v[14:17]
	v_mfma_f32_16x16x32_bf16 v[10:13], v[86:89], v[174:177], v[10:13]
	s_setprio 0
	s_barrier
	s_add_i32 s42, s42, s78
	v_lshl_add_u64 v[58:59], v[242:243], 0, s[22:23]
	s_mov_b32 m0, s42
	s_nop 0
	global_load_lds_dwordx4 v[58:59], off
	v_lshl_add_u64 v[58:59], v[244:245], 0, s[22:23]
	s_add_i32 m0, s42, 0x2000
	s_nop 0
	global_load_lds_dwordx4 v[58:59], off
	s_waitcnt vmcnt(6)
	s_barrier
	s_setprio 1
	v_mfma_f32_16x16x32_bf16 v[50:53], v[186:189], v[66:69], v[50:53]
	v_mfma_f32_16x16x32_bf16 v[86:89], v[190:193], v[70:73], v[50:53]
	v_mfma_f32_16x16x32_bf16 v[50:53], v[208:211], v[66:69], v[54:57]
	v_mfma_f32_16x16x32_bf16 v[38:41], v[186:189], v[74:77], v[38:41]
	v_mfma_f32_16x16x32_bf16 v[34:37], v[208:211], v[74:77], v[34:37]
	v_mfma_f32_16x16x32_bf16 v[22:25], v[186:189], v[146:149], v[22:25]
	v_mfma_f32_16x16x32_bf16 v[18:21], v[208:211], v[146:149], v[18:21]
	v_mfma_f32_16x16x32_bf16 v[6:9], v[186:189], v[170:173], v[6:9]
	v_mfma_f32_16x16x32_bf16 v[2:5], v[208:211], v[170:173], v[2:5]
	v_mfma_f32_16x16x32_bf16 v[82:85], v[232:235], v[70:73], v[50:53]
	v_mfma_f32_16x16x32_bf16 v[38:41], v[190:193], v[78:81], v[38:41]
	v_mfma_f32_16x16x32_bf16 v[34:37], v[232:235], v[78:81], v[34:37]
	v_mfma_f32_16x16x32_bf16 v[22:25], v[190:193], v[154:157], v[22:25]
	v_mfma_f32_16x16x32_bf16 v[18:21], v[232:235], v[154:157], v[18:21]
	v_mfma_f32_16x16x32_bf16 v[6:9], v[190:193], v[174:177], v[6:9]
	v_mfma_f32_16x16x32_bf16 v[2:5], v[232:235], v[174:177], v[2:5]
	s_setprio 0
	s_add_u32 s27, s27, 0x100
	s_addc_u32 s91, s91, 0
	s_add_u32 s36, s36, 0x100
	s_addc_u32 s37, s37, 0
	s_cmp_ge_u32 s92, s84
	s_mov_b32 s42, s92
	s_barrier
